# grid barrier: generation from loop counter, last local arriver adds to replicated per-XCD release counters, all workgroups poll own line (no TOP/TOPGEN relay); plus adaLN k-loop pipelining
# baseline (speedup 1.0000x reference)
; __device__ __forceinline__ unsigned xb_ld(unsigned* p)              { return __hip_atomic_load(p, __ATOMIC_RELAXED, __HIP_MEMORY_SCOPE_AGENT); }
; __device__ __forceinline__ unsigned xb_add(unsigned* p, unsigned v) { return __hip_atomic_fetch_add(p, v, __ATOMIC_RELAXED, __HIP_MEMORY_SCOPE_AGENT); }
; #define XB_SPIN(cond, bar) do { unsigned _sp = 0; while (cond) { __builtin_amdgcn_s_sleep(1); \
;     if ((++_sp & 255u) == 0u) { if (xb_ld(&(bar)[XB_TMO])) break; if (_sp > XB_SPIN_CAP) { atomicAdd(&(bar)[XB_TMO], 1u); break; } } } } while (0)
; __device__ __forceinline__ void xcd_barrier(const XcdBarrier& b) {
;     asm volatile("s_waitcnt vmcnt(0)" ::: "memory");
;     __syncthreads();
;     if (threadIdx.x == 0) {
;         unsigned* bar = b.bar;
;         __builtin_amdgcn_s_waitcnt(0);
;         unsigned nloc = b.st[0], nx = b.st[1];
;         if (nloc == 0u) { xcd_barrier_complete(bar, b.x, nloc, nx); b.st[0] = nloc; b.st[1] = nx; }
;         const unsigned old = xb_add(&bar[XB_XSUB(b.x)], 1u);
;         const unsigned gen = old / nloc;
;         if (old + 1u == (gen + 1u) * nloc) {
;             __builtin_amdgcn_fence(__ATOMIC_RELEASE, "agent");
;             asm volatile("s_waitcnt vmcnt(0)" ::: "memory");
;             const unsigned og = xb_add(&bar[XB_TOP], 1u);
;             const unsigned tg = og / nx;
;             if (og + 1u == (tg + 1u) * nx) xb_add(&bar[XB_TOPGEN], 1u);
;             else XB_SPIN(xb_ld(&bar[XB_TOPGEN]) == tg, bar);
;             __builtin_amdgcn_fence(__ATOMIC_ACQUIRE, "agent");
;             xb_add(&bar[XB_XGEN(b.x)], 1u);
;             asm volatile("s_waitcnt vmcnt(0)" ::: "memory");
;         } else {
;             XB_SPIN(xb_ld(&bar[XB_XGEN(b.x)]) == gen, bar);
;             __builtin_amdgcn_fence(__ATOMIC_ACQUIRE, "agent");
;             asm volatile("s_waitcnt vmcnt(0)" ::: "memory");
;         }
;     }
;     __syncthreads();
.LBB0_26:
	s_waitcnt lgkmcnt(0)
	v_readfirstlane_b32 s10, v2
	v_readfirstlane_b32 s11, v0
	v_readlane_b32 s12, v252, 47
	v_readlane_b32 s13, v252, 48
	v_readlane_b32 s6, v254, 51
	v_mov_b32_e32 v3, 1
	s_mul_i32 s14, s6, s10
	s_mul_i32 s15, s6, s11
	s_nop 4
	global_atomic_add v3, v97, v3, s[12:13] sc0
	s_waitcnt vmcnt(0)
	v_readfirstlane_b32 s6, v3
	s_add_i32 s6, s6, 1
	s_cmp_lg_u32 s6, s14
	s_cbranch_scc1 .Lxb_wait
	buffer_wbl2 sc1
	s_waitcnt vmcnt(0)
	s_add_u32 s12, s26, 0x2400
	s_addc_u32 s13, s27, 0
	v_mov_b32_e32 v3, 1
	global_atomic_add v97, v3, s[12:13]
	global_atomic_add v97, v3, s[12:13] offset:256
	global_atomic_add v97, v3, s[12:13] offset:512
	global_atomic_add v97, v3, s[12:13] offset:768
	global_atomic_add v97, v3, s[12:13] offset:1024
	global_atomic_add v97, v3, s[12:13] offset:1280
	global_atomic_add v97, v3, s[12:13] offset:1536
	global_atomic_add v97, v3, s[12:13] offset:1792
	global_atomic_add v97, v3, s[12:13] offset:2048
	global_atomic_add v97, v3, s[12:13] offset:2304
	global_atomic_add v97, v3, s[12:13] offset:2560
	global_atomic_add v97, v3, s[12:13] offset:2816
	global_atomic_add v97, v3, s[12:13] offset:3072
	global_atomic_add v97, v3, s[12:13] offset:3328
	global_atomic_add v97, v3, s[12:13] offset:3584
	global_atomic_add v97, v3, s[12:13] offset:3840
.Lxb_wait:
	v_readlane_b32 s12, v252, 49
	v_readlane_b32 s13, v252, 50
	s_mov_b32 s6, 0
	s_nop 4
.Lxb_spin:
	global_load_dword v3, v97, s[12:13] sc1
	s_waitcnt vmcnt(0)
	v_readfirstlane_b32 s14, v3
	s_sub_i32 s14, s14, s15
	s_cmp_ge_i32 s14, 0
	s_cbranch_scc1 .Lxb_done
	s_sleep 1
	s_add_i32 s6, s6, 1
	s_and_b32 s14, s6, 0xff
	s_cmp_lg_u32 s14, 0
	s_cbranch_scc1 .Lxb_spin
	v_readlane_b32 s10, v252, 5
	v_readlane_b32 s11, v252, 6
	s_nop 4
	global_load_dword v3, v97, s[10:11] sc1
	s_waitcnt vmcnt(0)
	v_readfirstlane_b32 s14, v3
	s_cmp_lg_u32 s14, 0
	s_cbranch_scc1 .Lxb_done
	s_cmp_lt_u32 s6, 0x40001
	s_cbranch_scc1 .Lxb_spin
	v_mov_b32_e32 v3, 1
	global_atomic_add v97, v3, s[10:11]
.Lxb_done:
	s_waitcnt vmcnt(0)
	buffer_inv sc1
	s_waitcnt vmcnt(0)

; DI float silu(float x) { return x * __builtin_amdgcn_rcpf(1.f + __expf(-x)); }
; DI void p0_phase(const Params& P, LAS unsigned char* lds, int gw, int NGW, int wave, int lane) {
;     ...
;     for (int it = gw; it < 2 * 16 * 48; it += NGW) {
;         const int cgp = it % 48, kc = (it / 48) % 16, l = it / 768, j0 = cgp * 256 + 4 * lane;
;         f32x4 a0 = {0.f, 0.f, 0.f, 0.f}, a1 = {0.f, 0.f, 0.f, 0.f};
;         const float* wp = P.w_ada + ((size_t)l * D + kc * 128) * NMOD + j0;
; #pragma unroll 8
;         for (int k = 0; k < 128; ++k) { const f32x4 w4 = *(const f32x4*)(wp + (size_t)k * NMOD);
;             const float c0 = silu(P.c[kc * 128 + k]), c1 = silu(P.c[D + kc * 128 + k]); a0 += w4 * c0; a1 += w4 * c1; }
.Ladaln_pair:
	s_mov_b32 s0, 0xfffdc000
	v_add_co_u32_e64 v120, s[0:1], s0, v14
	s_add_u32 s8, s13, s4
	s_nop 0
	v_addc_co_u32_e64 v121, s[0:1], -1, v15, s[0:1]
	s_mov_b32 s0, 0xfffe8000
	s_nop 0
	v_add_co_u32_e64 v124, s[0:1], s0, v14
	v_add_co_u32_e32 v116, vcc, 0xfffd0000, v14
	s_nop 0
	v_addc_co_u32_e64 v125, s[0:1], -1, v15, s[0:1]
	s_mov_b32 s0, 0xffff4000
	s_nop 0
	v_add_co_u32_e64 v128, s[0:1], s0, v14
	s_addc_u32 s9, s14, s5
	s_nop 0
	v_addc_co_u32_e64 v129, s[0:1], -1, v15, s[0:1]
	v_add_co_u32_e64 v132, s[0:1], s31, v14
	global_load_dwordx4 v[108:111], v[14:15], off
	s_nop 0
	v_addc_co_u32_e64 v133, s[0:1], 0, v15, s[0:1]
	s_mov_b32 s0, 0x18000
	s_nop 0
	v_add_co_u32_e64 v136, s[0:1], s0, v14
	v_addc_co_u32_e32 v117, vcc, -1, v15, vcc
	s_nop 0
	v_addc_co_u32_e64 v137, s[0:1], 0, v15, s[0:1]
	s_mov_b32 s0, 0x24000
	s_nop 0
	v_add_co_u32_e64 v140, s[0:1], s0, v14
	s_nop 1
	v_addc_co_u32_e64 v141, s[0:1], 0, v15, s[0:1]
	s_mov_b64 s[0:1], 0x60000
	global_load_dwordx4 v[120:123], v[120:121], off
	s_nop 0
	global_load_dwordx4 v[124:127], v[124:125], off
	s_nop 0
	global_load_dwordx4 v[128:131], v[128:129], off
	s_nop 0
	global_load_dwordx4 v[132:135], v[132:133], off
	s_nop 0
	global_load_dwordx4 v[136:139], v[136:137], off
	s_nop 0
	global_load_dwordx4 v[140:143], v[140:141], off
	v_lshl_add_u64 v[14:15], v[14:15], 0, s[0:1]
	global_load_dwordx4 v[144:147], v97, s[8:9]
	global_load_dwordx4 v[148:151], v231, s[8:9]
	global_load_dwordx4 v[152:155], v97, s[8:9] offset:16
	global_load_dwordx4 v[156:159], v[116:117], off
	s_add_u32 s0, s8, 0x2000
	s_addc_u32 s1, s9, 0
	global_load_dwordx4 v[160:163], v97, s[0:1] offset:16
	s_add_u32 s4, s4, 32
	s_addc_u32 s5, s5, 0
	s_waitcnt vmcnt(12)
	v_mul_f32_e32 v16, 0xbfb8aa3b, v44
	v_mul_f32_e32 v17, 0xbfb8aa3b, v48
	v_mul_f32_e32 v19, 0xbfb8aa3b, v45
	v_mul_f32_e32 v64, 0xbfb8aa3b, v49
	v_exp_f32_e32 v16, v16
	v_exp_f32_e32 v17, v17
	v_mul_f32_e32 v65, 0xbfb8aa3b, v46
	v_mul_f32_e32 v66, 0xbfb8aa3b, v50
	v_exp_f32_e32 v19, v19
	v_exp_f32_e32 v64, v64
	v_mul_f32_e32 v67, 0xbfb8aa3b, v47
	v_mul_f32_e32 v68, 0xbfb8aa3b, v51
	v_exp_f32_e32 v65, v65
	v_exp_f32_e32 v66, v66
	v_mul_f32_e32 v69, 0xbfb8aa3b, v52
	v_exp_f32_e32 v67, v67
	v_exp_f32_e32 v68, v68
	v_mul_f32_e32 v73, 0xbfb8aa3b, v60
	v_mul_f32_e32 v70, 0xbfb8aa3b, v53
	v_exp_f32_e32 v69, v69
	v_mul_f32_e32 v74, 0xbfb8aa3b, v61
	v_exp_f32_e32 v73, v73
	v_add_f32_e32 v16, 1.0, v16
	v_add_f32_e32 v17, 1.0, v17
	v_mul_f32_e32 v71, 0xbfb8aa3b, v54
	v_exp_f32_e32 v70, v70
	v_mul_f32_e32 v75, 0xbfb8aa3b, v62
	v_exp_f32_e32 v74, v74
	v_add_f32_e32 v19, 1.0, v19
	v_add_f32_e32 v64, 1.0, v64
	v_rcp_f32_e32 v16, v16
	v_rcp_f32_e32 v17, v17
	v_mul_f32_e32 v72, 0xbfb8aa3b, v55
	v_exp_f32_e32 v71, v71
	v_mul_f32_e32 v76, 0xbfb8aa3b, v63
	v_exp_f32_e32 v75, v75
	v_add_f32_e32 v65, 1.0, v65
	v_add_f32_e32 v66, 1.0, v66
	v_rcp_f32_e32 v19, v19
	v_rcp_f32_e32 v64, v64
	v_exp_f32_e32 v72, v72
	v_exp_f32_e32 v76, v76
	v_add_f32_e32 v67, 1.0, v67
	v_add_f32_e32 v68, 1.0, v68
	v_rcp_f32_e32 v65, v65
	v_rcp_f32_e32 v66, v66
	v_add_f32_e32 v69, 1.0, v69
	v_rcp_f32_e32 v67, v67
	v_rcp_f32_e32 v68, v68
	v_add_f32_e32 v73, 1.0, v73
	v_add_f32_e32 v70, 1.0, v70
	v_rcp_f32_e32 v69, v69
	v_add_f32_e32 v74, 1.0, v74
	v_rcp_f32_e32 v73, v73
	v_mul_f32_e32 v16, v44, v16
	v_mul_f32_e32 v44, v48, v17
	v_add_f32_e32 v71, 1.0, v71
	v_rcp_f32_e32 v70, v70
	v_add_f32_e32 v75, 1.0, v75
	v_rcp_f32_e32 v74, v74
	v_mul_f32_e32 v48, v45, v19
	v_mul_f32_e32 v64, v49, v64
	v_pk_fma_f32 v[4:5], v[56:57], v[16:17], v[4:5] op_sel_hi:[1,0,1]
	v_pk_fma_f32 v[6:7], v[58:59], v[16:17], v[6:7] op_sel_hi:[1,0,1]
	v_pk_fma_f32 v[0:1], v[56:57], v[44:45], v[0:1] op_sel_hi:[1,0,1]
	v_pk_fma_f32 v[2:3], v[58:59], v[44:45], v[2:3] op_sel_hi:[1,0,1]
	v_add_f32_e32 v72, 1.0, v72
	v_rcp_f32_e32 v71, v71
	v_add_f32_e32 v76, 1.0, v76
	v_rcp_f32_e32 v75, v75
	v_mul_f32_e32 v46, v46, v65
	v_mul_f32_e32 v50, v50, v66
	v_pk_fma_f32 v[6:7], v[22:23], v[48:49], v[6:7] op_sel_hi:[1,0,1]
	v_pk_fma_f32 v[4:5], v[20:21], v[48:49], v[4:5] op_sel_hi:[1,0,1]
	v_pk_fma_f32 v[2:3], v[22:23], v[64:65], v[2:3] op_sel_hi:[1,0,1]
	v_pk_fma_f32 v[0:1], v[20:21], v[64:65], v[0:1] op_sel_hi:[1,0,1]
	v_rcp_f32_e32 v72, v72
	v_rcp_f32_e32 v76, v76
	v_mul_f32_e32 v66, v47, v67
	v_mul_f32_e32 v68, v51, v68
	v_pk_fma_f32 v[6:7], v[26:27], v[46:47], v[6:7] op_sel_hi:[1,0,1]
	v_pk_fma_f32 v[4:5], v[24:25], v[46:47], v[4:5] op_sel_hi:[1,0,1]
	v_pk_fma_f32 v[2:3], v[26:27], v[50:51], v[2:3] op_sel_hi:[1,0,1]
	v_pk_fma_f32 v[0:1], v[24:25], v[50:51], v[0:1] op_sel_hi:[1,0,1]
	v_mul_f32_e32 v52, v52, v69
	v_mul_f32_e32 v16, v60, v73
	v_pk_fma_f32 v[6:7], v[30:31], v[66:67], v[6:7] op_sel_hi:[1,0,1]
	v_pk_fma_f32 v[4:5], v[28:29], v[66:67], v[4:5] op_sel_hi:[1,0,1]
	v_pk_fma_f32 v[2:3], v[30:31], v[68:69], v[2:3] op_sel_hi:[1,0,1]
	v_pk_fma_f32 v[0:1], v[28:29], v[68:69], v[0:1] op_sel_hi:[1,0,1]
	v_mul_f32_e32 v70, v53, v70
	v_mul_f32_e32 v20, v61, v74
	v_pk_fma_f32 v[6:7], v[10:11], v[52:53], v[6:7] op_sel_hi:[1,0,1]
	v_pk_fma_f32 v[4:5], v[8:9], v[52:53], v[4:5] op_sel_hi:[1,0,1]
	v_pk_fma_f32 v[2:3], v[10:11], v[16:17], v[2:3] op_sel_hi:[1,0,1]
	v_pk_fma_f32 v[0:1], v[8:9], v[16:17], v[0:1] op_sel_hi:[1,0,1]
	v_mul_f32_e32 v54, v54, v71
	v_mul_f32_e32 v22, v62, v75
	v_pk_fma_f32 v[6:7], v[34:35], v[70:71], v[6:7] op_sel_hi:[1,0,1]
	v_pk_fma_f32 v[4:5], v[32:33], v[70:71], v[4:5] op_sel_hi:[1,0,1]
	v_pk_fma_f32 v[2:3], v[34:35], v[20:21], v[2:3] op_sel_hi:[1,0,1]
	v_pk_fma_f32 v[0:1], v[32:33], v[20:21], v[0:1] op_sel_hi:[1,0,1]
	v_mul_f32_e32 v72, v55, v72
	v_mul_f32_e32 v44, v63, v76
	v_pk_fma_f32 v[6:7], v[38:39], v[54:55], v[6:7] op_sel_hi:[1,0,1]
	v_pk_fma_f32 v[4:5], v[36:37], v[54:55], v[4:5] op_sel_hi:[1,0,1]
	v_pk_fma_f32 v[2:3], v[38:39], v[22:23], v[2:3] op_sel_hi:[1,0,1]
	v_pk_fma_f32 v[0:1], v[36:37], v[22:23], v[0:1] op_sel_hi:[1,0,1]
	v_pk_fma_f32 v[6:7], v[42:43], v[72:73], v[6:7] op_sel_hi:[1,0,1]
	v_pk_fma_f32 v[4:5], v[40:41], v[72:73], v[4:5] op_sel_hi:[1,0,1]
	v_pk_fma_f32 v[2:3], v[42:43], v[44:45], v[2:3] op_sel_hi:[1,0,1]
	v_pk_fma_f32 v[0:1], v[40:41], v[44:45], v[0:1] op_sel_hi:[1,0,1]
	s_cmpk_eq_i32 s4, 0x200
	s_cbranch_scc1 .Ladaln_last
; DI float silu(float x) { return x * __builtin_amdgcn_rcpf(1.f + __expf(-x)); }
; DI void p0_phase(const Params& P, LAS unsigned char* lds, int gw, int NGW, int wave, int lane) {
;     ...
;         const float* wp = P.w_ada + ((size_t)l * D + kc * 128) * NMOD + j0;
; #pragma unroll 8
;         for (int k = 0; k < 128; ++k) { const f32x4 w4 = *(const f32x4*)(wp + (size_t)k * NMOD);
;             const float c0 = silu(P.c[kc * 128 + k]), c1 = silu(P.c[D + kc * 128 + k]); a0 += w4 * c0; a1 += w4 * c1; }
	s_mov_b32 s0, 0xfffdc000
	v_add_co_u32_e64 v20, s[0:1], s0, v14
	s_add_u32 s8, s13, s4
	s_nop 0
	v_addc_co_u32_e64 v21, s[0:1], -1, v15, s[0:1]
	s_mov_b32 s0, 0xfffe8000
	s_nop 0
	v_add_co_u32_e64 v24, s[0:1], s0, v14
	v_add_co_u32_e32 v16, vcc, 0xfffd0000, v14
	s_nop 0
	v_addc_co_u32_e64 v25, s[0:1], -1, v15, s[0:1]
	s_mov_b32 s0, 0xffff4000
	s_nop 0
	v_add_co_u32_e64 v28, s[0:1], s0, v14
	s_addc_u32 s9, s14, s5
	s_nop 0
	v_addc_co_u32_e64 v29, s[0:1], -1, v15, s[0:1]
	v_add_co_u32_e64 v32, s[0:1], s31, v14
	global_load_dwordx4 v[8:11], v[14:15], off
	s_nop 0
	v_addc_co_u32_e64 v33, s[0:1], 0, v15, s[0:1]
	s_mov_b32 s0, 0x18000
	s_nop 0
	v_add_co_u32_e64 v36, s[0:1], s0, v14
	v_addc_co_u32_e32 v17, vcc, -1, v15, vcc
	s_nop 0
	v_addc_co_u32_e64 v37, s[0:1], 0, v15, s[0:1]
	s_mov_b32 s0, 0x24000
	s_nop 0
	v_add_co_u32_e64 v40, s[0:1], s0, v14
	s_nop 1
	v_addc_co_u32_e64 v41, s[0:1], 0, v15, s[0:1]
	s_mov_b64 s[0:1], 0x60000
	global_load_dwordx4 v[20:23], v[20:21], off
	s_nop 0
	global_load_dwordx4 v[24:27], v[24:25], off
	s_nop 0
	global_load_dwordx4 v[28:31], v[28:29], off
	s_nop 0
	global_load_dwordx4 v[32:35], v[32:33], off
	s_nop 0
	global_load_dwordx4 v[36:39], v[36:37], off
	s_nop 0
	global_load_dwordx4 v[40:43], v[40:41], off
	v_lshl_add_u64 v[14:15], v[14:15], 0, s[0:1]
	global_load_dwordx4 v[44:47], v97, s[8:9]
	global_load_dwordx4 v[48:51], v231, s[8:9]
	global_load_dwordx4 v[52:55], v97, s[8:9] offset:16
	global_load_dwordx4 v[56:59], v[16:17], off
	s_add_u32 s0, s8, 0x2000
	s_addc_u32 s1, s9, 0
	global_load_dwordx4 v[60:63], v97, s[0:1] offset:16
	s_add_u32 s4, s4, 32
	s_addc_u32 s5, s5, 0
	s_waitcnt vmcnt(12)
	v_mul_f32_e32 v16, 0xbfb8aa3b, v144
	v_mul_f32_e32 v17, 0xbfb8aa3b, v148
	v_mul_f32_e32 v19, 0xbfb8aa3b, v145
	v_mul_f32_e32 v64, 0xbfb8aa3b, v149
	v_exp_f32_e32 v16, v16
	v_exp_f32_e32 v17, v17
	v_mul_f32_e32 v65, 0xbfb8aa3b, v146
	v_mul_f32_e32 v66, 0xbfb8aa3b, v150
	v_exp_f32_e32 v19, v19
	v_exp_f32_e32 v64, v64
	v_mul_f32_e32 v67, 0xbfb8aa3b, v147
	v_mul_f32_e32 v68, 0xbfb8aa3b, v151
	v_exp_f32_e32 v65, v65
	v_exp_f32_e32 v66, v66
	v_mul_f32_e32 v69, 0xbfb8aa3b, v152
	v_exp_f32_e32 v67, v67
	v_exp_f32_e32 v68, v68
	v_mul_f32_e32 v73, 0xbfb8aa3b, v160
	v_mul_f32_e32 v70, 0xbfb8aa3b, v153
	v_exp_f32_e32 v69, v69
	v_mul_f32_e32 v74, 0xbfb8aa3b, v161
	v_exp_f32_e32 v73, v73
	v_add_f32_e32 v16, 1.0, v16
	v_add_f32_e32 v17, 1.0, v17
	v_mul_f32_e32 v71, 0xbfb8aa3b, v154
	v_exp_f32_e32 v70, v70
	v_mul_f32_e32 v75, 0xbfb8aa3b, v162
	v_exp_f32_e32 v74, v74
	v_add_f32_e32 v19, 1.0, v19
	v_add_f32_e32 v64, 1.0, v64
	v_rcp_f32_e32 v16, v16
	v_rcp_f32_e32 v17, v17
	v_mul_f32_e32 v72, 0xbfb8aa3b, v155
	v_exp_f32_e32 v71, v71
	v_mul_f32_e32 v76, 0xbfb8aa3b, v163
	v_exp_f32_e32 v75, v75
	v_add_f32_e32 v65, 1.0, v65
	v_add_f32_e32 v66, 1.0, v66
	v_rcp_f32_e32 v19, v19
	v_rcp_f32_e32 v64, v64
	v_exp_f32_e32 v72, v72
	v_exp_f32_e32 v76, v76
	v_add_f32_e32 v67, 1.0, v67
	v_add_f32_e32 v68, 1.0, v68
	v_rcp_f32_e32 v65, v65
	v_rcp_f32_e32 v66, v66
	v_add_f32_e32 v69, 1.0, v69
	v_rcp_f32_e32 v67, v67
	v_rcp_f32_e32 v68, v68
	v_add_f32_e32 v73, 1.0, v73
	v_add_f32_e32 v70, 1.0, v70
	v_rcp_f32_e32 v69, v69
	v_add_f32_e32 v74, 1.0, v74
	v_rcp_f32_e32 v73, v73
	v_mul_f32_e32 v16, v144, v16
	v_mul_f32_e32 v144, v148, v17
	v_add_f32_e32 v71, 1.0, v71
	v_rcp_f32_e32 v70, v70
	v_add_f32_e32 v75, 1.0, v75
	v_rcp_f32_e32 v74, v74
	v_mul_f32_e32 v148, v145, v19
	v_mul_f32_e32 v64, v149, v64
	v_pk_fma_f32 v[4:5], v[156:157], v[16:17], v[4:5] op_sel_hi:[1,0,1]
	v_pk_fma_f32 v[6:7], v[158:159], v[16:17], v[6:7] op_sel_hi:[1,0,1]
	v_pk_fma_f32 v[0:1], v[156:157], v[144:145], v[0:1] op_sel_hi:[1,0,1]
	v_pk_fma_f32 v[2:3], v[158:159], v[144:145], v[2:3] op_sel_hi:[1,0,1]
	v_add_f32_e32 v72, 1.0, v72
	v_rcp_f32_e32 v71, v71
	v_add_f32_e32 v76, 1.0, v76
	v_rcp_f32_e32 v75, v75
	v_mul_f32_e32 v146, v146, v65
	v_mul_f32_e32 v150, v150, v66
	v_pk_fma_f32 v[6:7], v[122:123], v[148:149], v[6:7] op_sel_hi:[1,0,1]
	v_pk_fma_f32 v[4:5], v[120:121], v[148:149], v[4:5] op_sel_hi:[1,0,1]
	v_pk_fma_f32 v[2:3], v[122:123], v[64:65], v[2:3] op_sel_hi:[1,0,1]
	v_pk_fma_f32 v[0:1], v[120:121], v[64:65], v[0:1] op_sel_hi:[1,0,1]
	v_rcp_f32_e32 v72, v72
	v_rcp_f32_e32 v76, v76
	v_mul_f32_e32 v66, v147, v67
	v_mul_f32_e32 v68, v151, v68
	v_pk_fma_f32 v[6:7], v[126:127], v[146:147], v[6:7] op_sel_hi:[1,0,1]
	v_pk_fma_f32 v[4:5], v[124:125], v[146:147], v[4:5] op_sel_hi:[1,0,1]
	v_pk_fma_f32 v[2:3], v[126:127], v[150:151], v[2:3] op_sel_hi:[1,0,1]
	v_pk_fma_f32 v[0:1], v[124:125], v[150:151], v[0:1] op_sel_hi:[1,0,1]
	v_mul_f32_e32 v152, v152, v69
	v_mul_f32_e32 v16, v160, v73
	v_pk_fma_f32 v[6:7], v[130:131], v[66:67], v[6:7] op_sel_hi:[1,0,1]
	v_pk_fma_f32 v[4:5], v[128:129], v[66:67], v[4:5] op_sel_hi:[1,0,1]
	v_pk_fma_f32 v[2:3], v[130:131], v[68:69], v[2:3] op_sel_hi:[1,0,1]
	v_pk_fma_f32 v[0:1], v[128:129], v[68:69], v[0:1] op_sel_hi:[1,0,1]
	v_mul_f32_e32 v70, v153, v70
	v_mul_f32_e32 v120, v161, v74
	v_pk_fma_f32 v[6:7], v[110:111], v[152:153], v[6:7] op_sel_hi:[1,0,1]
	v_pk_fma_f32 v[4:5], v[108:109], v[152:153], v[4:5] op_sel_hi:[1,0,1]
	v_pk_fma_f32 v[2:3], v[110:111], v[16:17], v[2:3] op_sel_hi:[1,0,1]
	v_pk_fma_f32 v[0:1], v[108:109], v[16:17], v[0:1] op_sel_hi:[1,0,1]
	v_mul_f32_e32 v154, v154, v71
	v_mul_f32_e32 v122, v162, v75
	v_pk_fma_f32 v[6:7], v[134:135], v[70:71], v[6:7] op_sel_hi:[1,0,1]
	v_pk_fma_f32 v[4:5], v[132:133], v[70:71], v[4:5] op_sel_hi:[1,0,1]
	v_pk_fma_f32 v[2:3], v[134:135], v[120:121], v[2:3] op_sel_hi:[1,0,1]
	v_pk_fma_f32 v[0:1], v[132:133], v[120:121], v[0:1] op_sel_hi:[1,0,1]
	v_mul_f32_e32 v72, v155, v72
	v_mul_f32_e32 v144, v163, v76
	v_pk_fma_f32 v[6:7], v[138:139], v[154:155], v[6:7] op_sel_hi:[1,0,1]
	v_pk_fma_f32 v[4:5], v[136:137], v[154:155], v[4:5] op_sel_hi:[1,0,1]
	v_pk_fma_f32 v[2:3], v[138:139], v[122:123], v[2:3] op_sel_hi:[1,0,1]
	v_pk_fma_f32 v[0:1], v[136:137], v[122:123], v[0:1] op_sel_hi:[1,0,1]
	v_pk_fma_f32 v[6:7], v[142:143], v[72:73], v[6:7] op_sel_hi:[1,0,1]
	v_pk_fma_f32 v[4:5], v[140:141], v[72:73], v[4:5] op_sel_hi:[1,0,1]
	v_pk_fma_f32 v[2:3], v[142:143], v[144:145], v[2:3] op_sel_hi:[1,0,1]
	v_pk_fma_f32 v[0:1], v[140:141], v[144:145], v[0:1] op_sel_hi:[1,0,1]
	s_branch .Ladaln_pair
; DI float silu(float x) { return x * __builtin_amdgcn_rcpf(1.f + __expf(-x)); }
; DI void p0_phase(const Params& P, LAS unsigned char* lds, int gw, int NGW, int wave, int lane) {
;     ...
;         for (int k = 0; k < 128; ++k) { const f32x4 w4 = *(const f32x4*)(wp + (size_t)k * NMOD);
;             const float c0 = silu(P.c[kc * 128 + k]), c1 = silu(P.c[D + kc * 128 + k]); a0 += w4 * c0; a1 += w4 * c1; }
;         *(f32x4*)(MODP + ((size_t)(kc * 2 + l) * 2 + 0) * NMOD + j0) = a0;
;         *(f32x4*)(MODP + ((size_t)(kc * 2 + l) * 2 + 1) * NMOD + j0) = a1;
;     }
.Ladaln_last:
	s_waitcnt vmcnt(0)
	v_mul_f32_e32 v16, 0xbfb8aa3b, v144
	v_mul_f32_e32 v17, 0xbfb8aa3b, v148
	v_mul_f32_e32 v19, 0xbfb8aa3b, v145
	v_mul_f32_e32 v64, 0xbfb8aa3b, v149
	v_exp_f32_e32 v16, v16
	v_exp_f32_e32 v17, v17
	v_mul_f32_e32 v65, 0xbfb8aa3b, v146
	v_mul_f32_e32 v66, 0xbfb8aa3b, v150
	v_exp_f32_e32 v19, v19
	v_exp_f32_e32 v64, v64
	v_mul_f32_e32 v67, 0xbfb8aa3b, v147
	v_mul_f32_e32 v68, 0xbfb8aa3b, v151
	v_exp_f32_e32 v65, v65
	v_exp_f32_e32 v66, v66
	v_mul_f32_e32 v69, 0xbfb8aa3b, v152
	v_exp_f32_e32 v67, v67
	v_exp_f32_e32 v68, v68
	v_mul_f32_e32 v73, 0xbfb8aa3b, v160
	v_mul_f32_e32 v70, 0xbfb8aa3b, v153
	v_exp_f32_e32 v69, v69
	v_mul_f32_e32 v74, 0xbfb8aa3b, v161
	v_exp_f32_e32 v73, v73
	v_add_f32_e32 v16, 1.0, v16
	v_add_f32_e32 v17, 1.0, v17
	v_mul_f32_e32 v71, 0xbfb8aa3b, v154
	v_exp_f32_e32 v70, v70
	v_mul_f32_e32 v75, 0xbfb8aa3b, v162
	v_exp_f32_e32 v74, v74
	v_add_f32_e32 v19, 1.0, v19
	v_add_f32_e32 v64, 1.0, v64
	v_rcp_f32_e32 v16, v16
	v_rcp_f32_e32 v17, v17
	v_mul_f32_e32 v72, 0xbfb8aa3b, v155
	v_exp_f32_e32 v71, v71
	v_mul_f32_e32 v76, 0xbfb8aa3b, v163
	v_exp_f32_e32 v75, v75
	v_add_f32_e32 v65, 1.0, v65
	v_add_f32_e32 v66, 1.0, v66
	v_rcp_f32_e32 v19, v19
	v_rcp_f32_e32 v64, v64
	v_exp_f32_e32 v72, v72
	v_exp_f32_e32 v76, v76
	v_add_f32_e32 v67, 1.0, v67
	v_add_f32_e32 v68, 1.0, v68
	v_rcp_f32_e32 v65, v65
	v_rcp_f32_e32 v66, v66
	v_add_f32_e32 v69, 1.0, v69
	v_rcp_f32_e32 v67, v67
	v_rcp_f32_e32 v68, v68
	v_add_f32_e32 v73, 1.0, v73
	v_add_f32_e32 v70, 1.0, v70
	v_rcp_f32_e32 v69, v69
	v_add_f32_e32 v74, 1.0, v74
	v_rcp_f32_e32 v73, v73
	v_mul_f32_e32 v16, v144, v16
	v_mul_f32_e32 v144, v148, v17
	v_add_f32_e32 v71, 1.0, v71
	v_rcp_f32_e32 v70, v70
	v_add_f32_e32 v75, 1.0, v75
	v_rcp_f32_e32 v74, v74
	v_mul_f32_e32 v148, v145, v19
	v_mul_f32_e32 v64, v149, v64
	v_pk_fma_f32 v[4:5], v[156:157], v[16:17], v[4:5] op_sel_hi:[1,0,1]
	v_pk_fma_f32 v[6:7], v[158:159], v[16:17], v[6:7] op_sel_hi:[1,0,1]
	v_pk_fma_f32 v[0:1], v[156:157], v[144:145], v[0:1] op_sel_hi:[1,0,1]
	v_pk_fma_f32 v[2:3], v[158:159], v[144:145], v[2:3] op_sel_hi:[1,0,1]
	v_add_f32_e32 v72, 1.0, v72
	v_rcp_f32_e32 v71, v71
	v_add_f32_e32 v76, 1.0, v76
	v_rcp_f32_e32 v75, v75
	v_mul_f32_e32 v146, v146, v65
	v_mul_f32_e32 v150, v150, v66
	v_pk_fma_f32 v[6:7], v[122:123], v[148:149], v[6:7] op_sel_hi:[1,0,1]
	v_pk_fma_f32 v[4:5], v[120:121], v[148:149], v[4:5] op_sel_hi:[1,0,1]
	v_pk_fma_f32 v[2:3], v[122:123], v[64:65], v[2:3] op_sel_hi:[1,0,1]
	v_pk_fma_f32 v[0:1], v[120:121], v[64:65], v[0:1] op_sel_hi:[1,0,1]
	v_rcp_f32_e32 v72, v72
	v_rcp_f32_e32 v76, v76
	v_mul_f32_e32 v66, v147, v67
	v_mul_f32_e32 v68, v151, v68
	v_pk_fma_f32 v[6:7], v[126:127], v[146:147], v[6:7] op_sel_hi:[1,0,1]
	v_pk_fma_f32 v[4:5], v[124:125], v[146:147], v[4:5] op_sel_hi:[1,0,1]
	v_pk_fma_f32 v[2:3], v[126:127], v[150:151], v[2:3] op_sel_hi:[1,0,1]
	v_pk_fma_f32 v[0:1], v[124:125], v[150:151], v[0:1] op_sel_hi:[1,0,1]
	v_mul_f32_e32 v152, v152, v69
	v_mul_f32_e32 v16, v160, v73
	v_pk_fma_f32 v[6:7], v[130:131], v[66:67], v[6:7] op_sel_hi:[1,0,1]
	v_pk_fma_f32 v[4:5], v[128:129], v[66:67], v[4:5] op_sel_hi:[1,0,1]
	v_pk_fma_f32 v[2:3], v[130:131], v[68:69], v[2:3] op_sel_hi:[1,0,1]
	v_pk_fma_f32 v[0:1], v[128:129], v[68:69], v[0:1] op_sel_hi:[1,0,1]
	v_mul_f32_e32 v70, v153, v70
	v_mul_f32_e32 v120, v161, v74
	v_pk_fma_f32 v[6:7], v[110:111], v[152:153], v[6:7] op_sel_hi:[1,0,1]
	v_pk_fma_f32 v[4:5], v[108:109], v[152:153], v[4:5] op_sel_hi:[1,0,1]
	v_pk_fma_f32 v[2:3], v[110:111], v[16:17], v[2:3] op_sel_hi:[1,0,1]
	v_pk_fma_f32 v[0:1], v[108:109], v[16:17], v[0:1] op_sel_hi:[1,0,1]
	v_mul_f32_e32 v154, v154, v71
	v_mul_f32_e32 v122, v162, v75
	v_pk_fma_f32 v[6:7], v[134:135], v[70:71], v[6:7] op_sel_hi:[1,0,1]
	v_pk_fma_f32 v[4:5], v[132:133], v[70:71], v[4:5] op_sel_hi:[1,0,1]
	v_pk_fma_f32 v[2:3], v[134:135], v[120:121], v[2:3] op_sel_hi:[1,0,1]
	v_pk_fma_f32 v[0:1], v[132:133], v[120:121], v[0:1] op_sel_hi:[1,0,1]
	v_mul_f32_e32 v72, v155, v72
	v_mul_f32_e32 v144, v163, v76
	v_pk_fma_f32 v[6:7], v[138:139], v[154:155], v[6:7] op_sel_hi:[1,0,1]
	v_pk_fma_f32 v[4:5], v[136:137], v[154:155], v[4:5] op_sel_hi:[1,0,1]
	v_pk_fma_f32 v[2:3], v[138:139], v[122:123], v[2:3] op_sel_hi:[1,0,1]
	v_pk_fma_f32 v[0:1], v[136:137], v[122:123], v[0:1] op_sel_hi:[1,0,1]
	v_pk_fma_f32 v[6:7], v[142:143], v[72:73], v[6:7] op_sel_hi:[1,0,1]
	v_pk_fma_f32 v[4:5], v[140:141], v[72:73], v[4:5] op_sel_hi:[1,0,1]
	v_pk_fma_f32 v[2:3], v[142:143], v[144:145], v[2:3] op_sel_hi:[1,0,1]
	v_pk_fma_f32 v[0:1], v[140:141], v[144:145], v[0:1] op_sel_hi:[1,0,1]
	s_lshl_b32 s0, s11, 1
	s_add_i32 s0, s0, s12
	s_mul_hi_i32 s1, s0, 0x18000
	s_mul_i32 s0, s0, 0x18000
	s_add_u32 s0, s6, s0
	s_addc_u32 s1, s10, s1
	v_lshl_add_u64 v[8:9], v[12:13], 2, s[0:1]
	global_store_dwordx4 v[8:9], v[4:7], off
	s_add_i32 s18, s18, s23
	s_cmpk_gt_i32 s18, 0x5ff
	v_add_co_u32_e32 v4, vcc, 0xc000, v8
	s_nop 1
	v_addc_co_u32_e32 v5, vcc, 0, v9, vcc
	global_store_dwordx4 v[4:5], v[0:3], off
	s_cbranch_scc0 .LBB0_841
	s_getpc_b64 s[98:99]
